# v060: v056 + prompt MLA fast path uses packed f32 for score-max subtraction and pairwise row sums
# baseline (speedup 1.0000x reference)
.Lpa_A1_rjoin:
	v_mov_b32_e32 v250, v3
	v_mfma_f32_32x32x16_bf16 v[98:113], v[4:7], v[130:133], 0
	v_pk_add_f32 v[18:19], v[18:19], v[250:251] op_sel_hi:[1,0] neg_lo:[0,1] neg_hi:[0,1]
	v_exp_f32_e32 v18, v18
	v_exp_f32_e32 v19, v19
	v_mfma_f32_32x32x16_bf16 v[82:97], v[82:85], v[130:133], 0
	v_pk_add_f32 v[20:21], v[20:21], v[250:251] op_sel_hi:[1,0] neg_lo:[0,1] neg_hi:[0,1]
	v_exp_f32_e32 v20, v20
	v_exp_f32_e32 v21, v21
	v_mfma_f32_32x32x16_bf16 v[98:113], v[8:11], v[134:137], v[98:113]
	v_pk_add_f32 v[22:23], v[22:23], v[250:251] op_sel_hi:[1,0] neg_lo:[0,1] neg_hi:[0,1]
	v_exp_f32_e32 v22, v22
	v_mov_b64_e32 v[16:17], v[18:19]
	v_exp_f32_e32 v23, v23
	v_mfma_f32_32x32x16_bf16 v[82:97], v[214:217], v[134:137], v[82:97]
	v_pk_add_f32 v[24:25], v[24:25], v[250:251] op_sel_hi:[1,0] neg_lo:[0,1] neg_hi:[0,1]
	v_exp_f32_e32 v24, v24
	v_pk_add_f32 v[16:17], v[16:17], v[20:21]
	v_exp_f32_e32 v25, v25
	v_mfma_f32_32x32x16_bf16 v[98:113], v[12:15], v[138:141], v[98:113]
	v_pk_add_f32 v[26:27], v[26:27], v[250:251] op_sel_hi:[1,0] neg_lo:[0,1] neg_hi:[0,1]
	v_exp_f32_e32 v26, v26
	v_pk_add_f32 v[16:17], v[16:17], v[22:23]
	v_exp_f32_e32 v27, v27
	v_mfma_f32_32x32x16_bf16 v[82:97], v[218:221], v[138:141], v[82:97]
	v_pk_add_f32 v[28:29], v[28:29], v[250:251] op_sel_hi:[1,0] neg_lo:[0,1] neg_hi:[0,1]
	v_exp_f32_e32 v28, v28
	v_pk_add_f32 v[16:17], v[16:17], v[24:25]
	v_exp_f32_e32 v29, v29
	v_mfma_f32_32x32x16_bf16 v[98:113], v[188:191], v[142:145], v[98:113]
	v_pk_add_f32 v[30:31], v[30:31], v[250:251] op_sel_hi:[1,0] neg_lo:[0,1] neg_hi:[0,1]
	v_exp_f32_e32 v30, v30
	v_pk_add_f32 v[16:17], v[16:17], v[26:27]
	v_exp_f32_e32 v31, v31
	v_mfma_f32_32x32x16_bf16 v[82:97], v[222:225], v[142:145], v[82:97]
	v_pk_add_f32 v[32:33], v[32:33], v[250:251] op_sel_hi:[1,0] neg_lo:[0,1] neg_hi:[0,1]
	v_exp_f32_e32 v32, v32
	v_pk_add_f32 v[16:17], v[16:17], v[28:29]
	v_exp_f32_e32 v33, v33
	v_mfma_f32_32x32x16_bf16 v[98:113], v[192:195], v[146:149], v[98:113]
	v_pk_add_f32 v[34:35], v[34:35], v[250:251] op_sel_hi:[1,0] neg_lo:[0,1] neg_hi:[0,1]
	v_exp_f32_e32 v34, v34
	v_mfma_f32_32x32x16_bf16 v[82:97], v[226:229], v[146:149], v[82:97]
	v_pk_add_f32 v[16:17], v[16:17], v[30:31]
	v_exp_f32_e32 v35, v35
	v_mfma_f32_32x32x16_bf16 v[98:113], v[210:213], v[150:153], v[98:113]
	v_pk_add_f32 v[36:37], v[36:37], v[250:251] op_sel_hi:[1,0] neg_lo:[0,1] neg_hi:[0,1]
	v_exp_f32_e32 v36, v36
	v_mfma_f32_32x32x16_bf16 v[82:97], v[244:247], v[150:153], v[82:97]
	v_pk_add_f32 v[16:17], v[16:17], v[32:33]
	v_exp_f32_e32 v37, v37
	ds_read_b64_tr_b16 v[4:5], v177 offset:0
	ds_read_b64_tr_b16 v[6:7], v177 offset:1536
	ds_read_b64_tr_b16 v[8:9], v177 offset:64
	ds_read_b64_tr_b16 v[10:11], v177 offset:1600
	ds_read_b64_tr_b16 v[12:13], v177 offset:3072
	ds_read_b64_tr_b16 v[14:15], v177 offset:4608
	ds_read_b64_tr_b16 v[188:189], v177 offset:3136
	ds_read_b64_tr_b16 v[190:191], v177 offset:4672
	ds_read_b64_tr_b16 v[192:193], v177 offset:6144
	ds_read_b64_tr_b16 v[194:195], v177 offset:7680
	ds_read_b64_tr_b16 v[210:211], v177 offset:6208
	ds_read_b64_tr_b16 v[212:213], v177 offset:7744
	ds_read_b64_tr_b16 v[214:215], v177 offset:9216
	ds_read_b64_tr_b16 v[216:217], v177 offset:10752
	ds_read_b64_tr_b16 v[218:219], v177 offset:9280
	ds_read_b64_tr_b16 v[220:221], v177 offset:10816
	v_pk_add_f32 v[38:39], v[38:39], v[250:251] op_sel_hi:[1,0] neg_lo:[0,1] neg_hi:[0,1]
	v_exp_f32_e32 v38, v38
	v_pk_add_f32 v[16:17], v[16:17], v[34:35]
	v_exp_f32_e32 v39, v39
	v_pk_add_f32 v[40:41], v[40:41], v[250:251] op_sel_hi:[1,0] neg_lo:[0,1] neg_hi:[0,1]
	v_exp_f32_e32 v40, v40
	v_pk_add_f32 v[16:17], v[16:17], v[36:37]
	v_exp_f32_e32 v41, v41
	v_cvt_pk_bf16_f32 v222, v18, v19
	v_cvt_pk_bf16_f32 v223, v20, v21
	v_cvt_pk_bf16_f32 v224, v22, v23
	v_cvt_pk_bf16_f32 v225, v24, v25
	v_cvt_pk_bf16_f32 v226, v26, v27
	v_cvt_pk_bf16_f32 v227, v28, v29
	v_cvt_pk_bf16_f32 v228, v30, v31
	v_cvt_pk_bf16_f32 v229, v32, v33
	v_cvt_pk_bf16_f32 v244, v34, v35
	v_cvt_pk_bf16_f32 v245, v36, v37
	v_cvt_pk_bf16_f32 v246, v38, v39
	v_cvt_pk_bf16_f32 v247, v40, v41
	s_waitcnt lgkmcnt(0)
	v_mfma_f32_32x32x16_bf16 v[66:81], v[4:7], v[222:225], v[66:81]
	v_pk_add_f32 v[42:43], v[42:43], v[250:251] op_sel_hi:[1,0] neg_lo:[0,1] neg_hi:[0,1]
	v_exp_f32_e32 v42, v42
	v_pk_add_f32 v[16:17], v[16:17], v[38:39]
	v_exp_f32_e32 v43, v43
	v_mfma_f32_32x32x16_bf16 v[50:65], v[8:11], v[222:225], v[50:65]
	v_pk_add_f32 v[44:45], v[44:45], v[250:251] op_sel_hi:[1,0] neg_lo:[0,1] neg_hi:[0,1]
	v_exp_f32_e32 v44, v44
	v_pk_add_f32 v[16:17], v[16:17], v[40:41]
	v_exp_f32_e32 v45, v45
	v_mfma_f32_32x32x16_bf16 v[66:81], v[12:15], v[226:229], v[66:81]
	v_pk_add_f32 v[46:47], v[46:47], v[250:251] op_sel_hi:[1,0] neg_lo:[0,1] neg_hi:[0,1]
	v_exp_f32_e32 v46, v46
	v_pk_add_f32 v[16:17], v[16:17], v[42:43]
	v_exp_f32_e32 v47, v47
	v_mfma_f32_32x32x16_bf16 v[50:65], v[188:191], v[226:229], v[50:65]
	v_pk_add_f32 v[48:49], v[48:49], v[250:251] op_sel_hi:[1,0] neg_lo:[0,1] neg_hi:[0,1]
	v_exp_f32_e32 v48, v48
	v_pk_add_f32 v[16:17], v[16:17], v[44:45]
	v_exp_f32_e32 v49, v49
	v_mfma_f32_32x32x16_bf16 v[66:81], v[192:195], v[244:247], v[66:81]
	v_pk_add_f32 v[16:17], v[16:17], v[46:47]
	v_pk_add_f32 v[16:17], v[16:17], v[48:49]
	v_add_f32_e32 v16, v16, v17
	v_fmac_f32_e32 v16, v185, v232
	v_mov_b32_e32 v185, v16
	v_mov_b32_e32 v186, v3
	v_mfma_f32_32x32x16_bf16 v[50:65], v[210:213], v[244:247], v[50:65]
	v_cvt_pk_bf16_f32 v248, v42, v43
	v_cvt_pk_bf16_f32 v249, v44, v45
	v_cvt_pk_bf16_f32 v250, v46, v47
	v_cvt_pk_bf16_f32 v251, v48, v49
	s_nop 1
	v_mfma_f32_32x32x16_bf16 v[66:81], v[214:217], v[248:251], v[66:81]
	v_mfma_f32_32x32x16_bf16 v[50:65], v[218:221], v[248:251], v[50:65]
	s_branch .LBB0_1194

.Lpa_A2_rjoin:
	v_mov_b32_e32 v250, v3
	v_mfma_f32_32x32x16_bf16 v[18:33], v[4:7], v[130:133], 0
	v_pk_add_f32 v[98:99], v[98:99], v[250:251] op_sel_hi:[1,0] neg_lo:[0,1] neg_hi:[0,1]
	v_exp_f32_e32 v98, v98
	v_exp_f32_e32 v99, v99
	v_mfma_f32_32x32x16_bf16 v[34:49], v[34:37], v[130:133], 0
	v_pk_add_f32 v[100:101], v[100:101], v[250:251] op_sel_hi:[1,0] neg_lo:[0,1] neg_hi:[0,1]
	v_exp_f32_e32 v100, v100
	v_exp_f32_e32 v101, v101
	v_mfma_f32_32x32x16_bf16 v[18:33], v[8:11], v[134:137], v[18:33]
	v_pk_add_f32 v[102:103], v[102:103], v[250:251] op_sel_hi:[1,0] neg_lo:[0,1] neg_hi:[0,1]
	v_exp_f32_e32 v102, v102
	v_mov_b64_e32 v[16:17], v[98:99]
	v_exp_f32_e32 v103, v103
	v_mfma_f32_32x32x16_bf16 v[34:49], v[214:217], v[134:137], v[34:49]
	v_pk_add_f32 v[104:105], v[104:105], v[250:251] op_sel_hi:[1,0] neg_lo:[0,1] neg_hi:[0,1]
	v_exp_f32_e32 v104, v104
	v_pk_add_f32 v[16:17], v[16:17], v[100:101]
	v_exp_f32_e32 v105, v105
	v_mfma_f32_32x32x16_bf16 v[18:33], v[12:15], v[138:141], v[18:33]
	v_pk_add_f32 v[106:107], v[106:107], v[250:251] op_sel_hi:[1,0] neg_lo:[0,1] neg_hi:[0,1]
	v_exp_f32_e32 v106, v106
	v_pk_add_f32 v[16:17], v[16:17], v[102:103]
	v_exp_f32_e32 v107, v107
	v_mfma_f32_32x32x16_bf16 v[34:49], v[218:221], v[138:141], v[34:49]
	v_pk_add_f32 v[108:109], v[108:109], v[250:251] op_sel_hi:[1,0] neg_lo:[0,1] neg_hi:[0,1]
	v_exp_f32_e32 v108, v108
	v_pk_add_f32 v[16:17], v[16:17], v[104:105]
	v_exp_f32_e32 v109, v109
	v_mfma_f32_32x32x16_bf16 v[18:33], v[188:191], v[142:145], v[18:33]
	v_pk_add_f32 v[110:111], v[110:111], v[250:251] op_sel_hi:[1,0] neg_lo:[0,1] neg_hi:[0,1]
	v_exp_f32_e32 v110, v110
	v_pk_add_f32 v[16:17], v[16:17], v[106:107]
	v_exp_f32_e32 v111, v111
	v_mfma_f32_32x32x16_bf16 v[34:49], v[222:225], v[142:145], v[34:49]
	v_pk_add_f32 v[112:113], v[112:113], v[250:251] op_sel_hi:[1,0] neg_lo:[0,1] neg_hi:[0,1]
	v_exp_f32_e32 v112, v112
	v_pk_add_f32 v[16:17], v[16:17], v[108:109]
	v_exp_f32_e32 v113, v113
	v_mfma_f32_32x32x16_bf16 v[18:33], v[192:195], v[146:149], v[18:33]
	v_pk_add_f32 v[82:83], v[82:83], v[250:251] op_sel_hi:[1,0] neg_lo:[0,1] neg_hi:[0,1]
	v_exp_f32_e32 v82, v82
	v_mfma_f32_32x32x16_bf16 v[34:49], v[226:229], v[146:149], v[34:49]
	v_pk_add_f32 v[16:17], v[16:17], v[110:111]
	v_exp_f32_e32 v83, v83
	v_mfma_f32_32x32x16_bf16 v[18:33], v[210:213], v[150:153], v[18:33]
	v_pk_add_f32 v[84:85], v[84:85], v[250:251] op_sel_hi:[1,0] neg_lo:[0,1] neg_hi:[0,1]
	v_exp_f32_e32 v84, v84
	v_mfma_f32_32x32x16_bf16 v[34:49], v[244:247], v[150:153], v[34:49]
	v_pk_add_f32 v[16:17], v[16:17], v[112:113]
	v_exp_f32_e32 v85, v85
	ds_read_b64_tr_b16 v[4:5], v178 offset:0
	ds_read_b64_tr_b16 v[6:7], v178 offset:1536
	ds_read_b64_tr_b16 v[8:9], v178 offset:64
	ds_read_b64_tr_b16 v[10:11], v178 offset:1600
	ds_read_b64_tr_b16 v[12:13], v178 offset:3072
	ds_read_b64_tr_b16 v[14:15], v178 offset:4608
	ds_read_b64_tr_b16 v[188:189], v178 offset:3136
	ds_read_b64_tr_b16 v[190:191], v178 offset:4672
	ds_read_b64_tr_b16 v[192:193], v178 offset:6144
	ds_read_b64_tr_b16 v[194:195], v178 offset:7680
	ds_read_b64_tr_b16 v[210:211], v178 offset:6208
	ds_read_b64_tr_b16 v[212:213], v178 offset:7744
	ds_read_b64_tr_b16 v[214:215], v178 offset:9216
	ds_read_b64_tr_b16 v[216:217], v178 offset:10752
	ds_read_b64_tr_b16 v[218:219], v178 offset:9280
	ds_read_b64_tr_b16 v[220:221], v178 offset:10816
	v_pk_add_f32 v[86:87], v[86:87], v[250:251] op_sel_hi:[1,0] neg_lo:[0,1] neg_hi:[0,1]
	v_exp_f32_e32 v86, v86
	v_pk_add_f32 v[16:17], v[16:17], v[82:83]
	v_exp_f32_e32 v87, v87
	v_pk_add_f32 v[88:89], v[88:89], v[250:251] op_sel_hi:[1,0] neg_lo:[0,1] neg_hi:[0,1]
	v_exp_f32_e32 v88, v88
	v_pk_add_f32 v[16:17], v[16:17], v[84:85]
	v_exp_f32_e32 v89, v89
	v_cvt_pk_bf16_f32 v222, v98, v99
	v_cvt_pk_bf16_f32 v223, v100, v101
	v_cvt_pk_bf16_f32 v224, v102, v103
	v_cvt_pk_bf16_f32 v225, v104, v105
	v_cvt_pk_bf16_f32 v226, v106, v107
	v_cvt_pk_bf16_f32 v227, v108, v109
	v_cvt_pk_bf16_f32 v228, v110, v111
	v_cvt_pk_bf16_f32 v229, v112, v113
	v_cvt_pk_bf16_f32 v244, v82, v83
	v_cvt_pk_bf16_f32 v245, v84, v85
	v_cvt_pk_bf16_f32 v246, v86, v87
	v_cvt_pk_bf16_f32 v247, v88, v89
	s_waitcnt lgkmcnt(0)
	v_mfma_f32_32x32x16_bf16 v[66:81], v[4:7], v[222:225], v[66:81]
	v_pk_add_f32 v[90:91], v[90:91], v[250:251] op_sel_hi:[1,0] neg_lo:[0,1] neg_hi:[0,1]
	v_exp_f32_e32 v90, v90
	v_pk_add_f32 v[16:17], v[16:17], v[86:87]
	v_exp_f32_e32 v91, v91
	v_mfma_f32_32x32x16_bf16 v[50:65], v[8:11], v[222:225], v[50:65]
	v_pk_add_f32 v[92:93], v[92:93], v[250:251] op_sel_hi:[1,0] neg_lo:[0,1] neg_hi:[0,1]
	v_exp_f32_e32 v92, v92
	v_pk_add_f32 v[16:17], v[16:17], v[88:89]
	v_exp_f32_e32 v93, v93
	v_mfma_f32_32x32x16_bf16 v[66:81], v[12:15], v[226:229], v[66:81]
	v_pk_add_f32 v[94:95], v[94:95], v[250:251] op_sel_hi:[1,0] neg_lo:[0,1] neg_hi:[0,1]
	v_exp_f32_e32 v94, v94
	v_pk_add_f32 v[16:17], v[16:17], v[90:91]
	v_exp_f32_e32 v95, v95
	v_mfma_f32_32x32x16_bf16 v[50:65], v[188:191], v[226:229], v[50:65]
	v_pk_add_f32 v[96:97], v[96:97], v[250:251] op_sel_hi:[1,0] neg_lo:[0,1] neg_hi:[0,1]
	v_exp_f32_e32 v96, v96
	v_pk_add_f32 v[16:17], v[16:17], v[92:93]
	v_exp_f32_e32 v97, v97
	v_mfma_f32_32x32x16_bf16 v[66:81], v[192:195], v[244:247], v[66:81]
	v_pk_add_f32 v[16:17], v[16:17], v[94:95]
	v_pk_add_f32 v[16:17], v[16:17], v[96:97]
	v_add_f32_e32 v16, v16, v17
	v_fmac_f32_e32 v16, v185, v232
	v_mov_b32_e32 v185, v16
	v_mov_b32_e32 v186, v3
	v_mfma_f32_32x32x16_bf16 v[50:65], v[210:213], v[244:247], v[50:65]
	v_cvt_pk_bf16_f32 v248, v90, v91
	v_cvt_pk_bf16_f32 v249, v92, v93
	v_cvt_pk_bf16_f32 v250, v94, v95
	v_cvt_pk_bf16_f32 v251, v96, v97
	s_nop 1
	v_mfma_f32_32x32x16_bf16 v[66:81], v[214:217], v[248:251], v[66:81]
	v_mfma_f32_32x32x16_bf16 v[50:65], v[218:221], v[248:251], v[50:65]
	s_branch .LBB0_1217
